# all K=1024/4096 side-GEMM k-loops: coalesced loads + ds_bpermute, k-steps prefetched in batches of 3 (Dq, HgIn, Wo x2, Down, KvQ) on top of v36
# speedup vs baseline: 1.0123x; 1.0021x over previous
.LBB0_273:
	v_mbcnt_lo_u32_b32 v212, -1, 0
	v_mbcnt_hi_u32_b32 v212, -1, v212
	v_lshrrev_b32_e32 v214, 2, v212
	v_and_b32_e32 v215, 15, v212
	v_sub_u32_e32 v214, v214, v215
	v_mul_i32_i24_e32 v214, 0x800, v214
	v_lshlrev_b32_e32 v216, 4, v215
	v_and_b32_e32 v215, 3, v212
	v_lshrrev_b32_e32 v212, 4, v212
	v_sub_u32_e32 v215, v215, v212
	v_lshl_add_u32 v214, v215, 4, v214
	v_lshl_add_u32 v216, v212, 2, v216
	v_ashrrev_i32_e32 v215, 31, v214
	s_lshl_b32 s6, s0, 1
	s_mov_b32 s7, 0
	v_lshl_add_u64 v[218:219], v[82:83], 0, v[214:215]
	v_lshl_add_u64 v[214:215], v[80:81], 0, v[214:215]
	v_lshl_add_u64 v[218:219], v[218:219], 0, s[6:7]
	v_lshl_add_u64 v[214:215], v[214:215], 0, s[6:7]
	s_mov_b64 s[8:9], 0x8000
	global_load_dwordx4 v[76:79], v[218:219], off
	global_load_dwordx4 v[96:99], v[218:219], off offset:512
	global_load_dwordx4 v[100:103], v[218:219], off offset:1024
	s_and_b64 vcc, exec, s[28:29]
	s_cbranch_vccz .Lsk273_b0_ld0
	global_load_dwordx4 v[104:107], v[214:215], off
	global_load_dwordx4 v[108:111], v[214:215], off offset:512
	global_load_dwordx4 v[112:115], v[214:215], off offset:1024
.Lsk273_b0_ld0:
	v_lshl_add_u64 v[228:229], v[214:215], 0, s[8:9]
	s_and_b64 vcc, exec, s[30:31]
	s_cbranch_vccz .Lsk273_b0_ld1
	global_load_dwordx4 v[116:119], v[228:229], off
	global_load_dwordx4 v[120:123], v[228:229], off offset:512
	global_load_dwordx4 v[124:127], v[228:229], off offset:1024
.Lsk273_b0_ld1:
	v_lshl_add_u64 v[230:231], v[228:229], 0, s[8:9]
	s_and_b64 vcc, exec, s[80:81]
	s_cbranch_vccz .Lsk273_b0_ld2
	global_load_dwordx4 v[128:131], v[230:231], off
	global_load_dwordx4 v[132:135], v[230:231], off offset:512
	global_load_dwordx4 v[136:139], v[230:231], off offset:1024
.Lsk273_b0_ld2:
	v_lshl_add_u64 v[228:229], v[230:231], 0, s[8:9]
	s_and_b64 vcc, exec, s[82:83]
	s_cbranch_vccz .Lsk273_b0_ld3
	global_load_dwordx4 v[140:143], v[228:229], off
	global_load_dwordx4 v[144:147], v[228:229], off offset:512
	global_load_dwordx4 v[148:151], v[228:229], off offset:1024
.Lsk273_b0_ld3:
	v_lshl_add_u64 v[230:231], v[228:229], 0, s[8:9]
	s_and_b64 vcc, exec, s[84:85]
	s_cbranch_vccz .Lsk273_b0_ld4
	global_load_dwordx4 v[152:155], v[230:231], off
	global_load_dwordx4 v[156:159], v[230:231], off offset:512
	global_load_dwordx4 v[160:163], v[230:231], off offset:1024
.Lsk273_b0_ld4:
	v_lshl_add_u64 v[228:229], v[230:231], 0, s[8:9]
	s_and_b64 vcc, exec, s[86:87]
	s_cbranch_vccz .Lsk273_b0_ld5
	global_load_dwordx4 v[164:167], v[228:229], off
	global_load_dwordx4 v[168:171], v[228:229], off offset:512
	global_load_dwordx4 v[172:175], v[228:229], off offset:1024
.Lsk273_b0_ld5:
	v_lshl_add_u64 v[230:231], v[228:229], 0, s[8:9]
	s_and_b64 vcc, exec, s[88:89]
	s_cbranch_vccz .Lsk273_b0_ld6
	global_load_dwordx4 v[176:179], v[230:231], off
	global_load_dwordx4 v[180:183], v[230:231], off offset:512
	global_load_dwordx4 v[184:187], v[230:231], off offset:1024
.Lsk273_b0_ld6:
	v_lshl_add_u64 v[228:229], v[230:231], 0, s[8:9]
	s_and_b64 vcc, exec, s[90:91]
	s_cbranch_vccz .Lsk273_b0_ld7
	global_load_dwordx4 v[188:191], v[228:229], off
	global_load_dwordx4 v[192:195], v[228:229], off offset:512
	global_load_dwordx4 v[196:199], v[228:229], off offset:1024
.Lsk273_b0_ld7:
	v_lshl_add_u64 v[230:231], v[228:229], 0, s[8:9]
	s_and_b64 vcc, exec, s[70:71]
	s_cbranch_vccz .Lsk273_b0_ld8
	global_load_dwordx4 v[200:203], v[230:231], off
	global_load_dwordx4 v[204:207], v[230:231], off offset:512
	global_load_dwordx4 v[208:211], v[230:231], off offset:1024
.Lsk273_b0_ld8:
	s_waitcnt vmcnt(0)
	ds_bpermute_b32 v76, v216, v76
	ds_bpermute_b32 v77, v216, v77
	ds_bpermute_b32 v78, v216, v78
	ds_bpermute_b32 v79, v216, v79
	ds_bpermute_b32 v96, v216, v96
	ds_bpermute_b32 v97, v216, v97
	ds_bpermute_b32 v98, v216, v98
	ds_bpermute_b32 v99, v216, v99
	ds_bpermute_b32 v100, v216, v100
	ds_bpermute_b32 v101, v216, v101
	ds_bpermute_b32 v102, v216, v102
	ds_bpermute_b32 v103, v216, v103
	s_and_b64 vcc, exec, s[28:29]
	s_cbranch_vccz .Lsk273_b0_mm0
	ds_bpermute_b32 v104, v216, v104
	ds_bpermute_b32 v105, v216, v105
	ds_bpermute_b32 v106, v216, v106
	ds_bpermute_b32 v107, v216, v107
	ds_bpermute_b32 v108, v216, v108
	ds_bpermute_b32 v109, v216, v109
	ds_bpermute_b32 v110, v216, v110
	ds_bpermute_b32 v111, v216, v111
	ds_bpermute_b32 v112, v216, v112
	ds_bpermute_b32 v113, v216, v113
	ds_bpermute_b32 v114, v216, v114
	ds_bpermute_b32 v115, v216, v115
	s_waitcnt lgkmcnt(0)
	v_mfma_f32_16x16x32_bf16 v[72:75], v[76:79], v[104:107], v[72:75]
	v_mfma_f32_16x16x32_bf16 v[72:75], v[96:99], v[108:111], v[72:75]
	v_mfma_f32_16x16x32_bf16 v[72:75], v[100:103], v[112:115], v[72:75]
.Lsk273_b0_mm0:
	s_and_b64 vcc, exec, s[30:31]
	s_cbranch_vccz .Lsk273_b0_mm1
	ds_bpermute_b32 v116, v216, v116
	ds_bpermute_b32 v117, v216, v117
	ds_bpermute_b32 v118, v216, v118
	ds_bpermute_b32 v119, v216, v119
	ds_bpermute_b32 v120, v216, v120
	ds_bpermute_b32 v121, v216, v121
	ds_bpermute_b32 v122, v216, v122
	ds_bpermute_b32 v123, v216, v123
	ds_bpermute_b32 v124, v216, v124
	ds_bpermute_b32 v125, v216, v125
	ds_bpermute_b32 v126, v216, v126
	ds_bpermute_b32 v127, v216, v127
	s_waitcnt lgkmcnt(0)
	v_mfma_f32_16x16x32_bf16 v[68:71], v[76:79], v[116:119], v[68:71]
	v_mfma_f32_16x16x32_bf16 v[68:71], v[96:99], v[120:123], v[68:71]
	v_mfma_f32_16x16x32_bf16 v[68:71], v[100:103], v[124:127], v[68:71]
.Lsk273_b0_mm1:
	s_and_b64 vcc, exec, s[80:81]
	s_cbranch_vccz .Lsk273_b0_mm2
	ds_bpermute_b32 v128, v216, v128
	ds_bpermute_b32 v129, v216, v129
	ds_bpermute_b32 v130, v216, v130
	ds_bpermute_b32 v131, v216, v131
	ds_bpermute_b32 v132, v216, v132
	ds_bpermute_b32 v133, v216, v133
	ds_bpermute_b32 v134, v216, v134
	ds_bpermute_b32 v135, v216, v135
	ds_bpermute_b32 v136, v216, v136
	ds_bpermute_b32 v137, v216, v137
	ds_bpermute_b32 v138, v216, v138
	ds_bpermute_b32 v139, v216, v139
	s_waitcnt lgkmcnt(0)
	v_mfma_f32_16x16x32_bf16 v[64:67], v[76:79], v[128:131], v[64:67]
	v_mfma_f32_16x16x32_bf16 v[64:67], v[96:99], v[132:135], v[64:67]
	v_mfma_f32_16x16x32_bf16 v[64:67], v[100:103], v[136:139], v[64:67]
.Lsk273_b0_mm2:
	s_and_b64 vcc, exec, s[82:83]
	s_cbranch_vccz .Lsk273_b0_mm3
	ds_bpermute_b32 v140, v216, v140
	ds_bpermute_b32 v141, v216, v141
	ds_bpermute_b32 v142, v216, v142
	ds_bpermute_b32 v143, v216, v143
	ds_bpermute_b32 v144, v216, v144
	ds_bpermute_b32 v145, v216, v145
	ds_bpermute_b32 v146, v216, v146
	ds_bpermute_b32 v147, v216, v147
	ds_bpermute_b32 v148, v216, v148
	ds_bpermute_b32 v149, v216, v149
	ds_bpermute_b32 v150, v216, v150
	ds_bpermute_b32 v151, v216, v151
	s_waitcnt lgkmcnt(0)
	v_mfma_f32_16x16x32_bf16 v[60:63], v[76:79], v[140:143], v[60:63]
	v_mfma_f32_16x16x32_bf16 v[60:63], v[96:99], v[144:147], v[60:63]
	v_mfma_f32_16x16x32_bf16 v[60:63], v[100:103], v[148:151], v[60:63]
.Lsk273_b0_mm3:
	s_and_b64 vcc, exec, s[84:85]
	s_cbranch_vccz .Lsk273_b0_mm4
	ds_bpermute_b32 v152, v216, v152
	ds_bpermute_b32 v153, v216, v153
	ds_bpermute_b32 v154, v216, v154
	ds_bpermute_b32 v155, v216, v155
	ds_bpermute_b32 v156, v216, v156
	ds_bpermute_b32 v157, v216, v157
	ds_bpermute_b32 v158, v216, v158
	ds_bpermute_b32 v159, v216, v159
	ds_bpermute_b32 v160, v216, v160
	ds_bpermute_b32 v161, v216, v161
	ds_bpermute_b32 v162, v216, v162
	ds_bpermute_b32 v163, v216, v163
	s_waitcnt lgkmcnt(0)
	v_mfma_f32_16x16x32_bf16 v[56:59], v[76:79], v[152:155], v[56:59]
	v_mfma_f32_16x16x32_bf16 v[56:59], v[96:99], v[156:159], v[56:59]
	v_mfma_f32_16x16x32_bf16 v[56:59], v[100:103], v[160:163], v[56:59]
.Lsk273_b0_mm4:
	s_and_b64 vcc, exec, s[86:87]
	s_cbranch_vccz .Lsk273_b0_mm5
	ds_bpermute_b32 v164, v216, v164
	ds_bpermute_b32 v165, v216, v165
	ds_bpermute_b32 v166, v216, v166
	ds_bpermute_b32 v167, v216, v167
	ds_bpermute_b32 v168, v216, v168
	ds_bpermute_b32 v169, v216, v169
	ds_bpermute_b32 v170, v216, v170
	ds_bpermute_b32 v171, v216, v171
	ds_bpermute_b32 v172, v216, v172
	ds_bpermute_b32 v173, v216, v173
	ds_bpermute_b32 v174, v216, v174
	ds_bpermute_b32 v175, v216, v175
	s_waitcnt lgkmcnt(0)
	v_mfma_f32_16x16x32_bf16 v[52:55], v[76:79], v[164:167], v[52:55]
	v_mfma_f32_16x16x32_bf16 v[52:55], v[96:99], v[168:171], v[52:55]
	v_mfma_f32_16x16x32_bf16 v[52:55], v[100:103], v[172:175], v[52:55]
.Lsk273_b0_mm5:
	s_and_b64 vcc, exec, s[88:89]
	s_cbranch_vccz .Lsk273_b0_mm6
	ds_bpermute_b32 v176, v216, v176
	ds_bpermute_b32 v177, v216, v177
	ds_bpermute_b32 v178, v216, v178
	ds_bpermute_b32 v179, v216, v179
	ds_bpermute_b32 v180, v216, v180
	ds_bpermute_b32 v181, v216, v181
	ds_bpermute_b32 v182, v216, v182
	ds_bpermute_b32 v183, v216, v183
	ds_bpermute_b32 v184, v216, v184
	ds_bpermute_b32 v185, v216, v185
	ds_bpermute_b32 v186, v216, v186
	ds_bpermute_b32 v187, v216, v187
	s_waitcnt lgkmcnt(0)
	v_mfma_f32_16x16x32_bf16 v[48:51], v[76:79], v[176:179], v[48:51]
	v_mfma_f32_16x16x32_bf16 v[48:51], v[96:99], v[180:183], v[48:51]
	v_mfma_f32_16x16x32_bf16 v[48:51], v[100:103], v[184:187], v[48:51]
.Lsk273_b0_mm6:
	s_and_b64 vcc, exec, s[90:91]
	s_cbranch_vccz .Lsk273_b0_mm7
	ds_bpermute_b32 v188, v216, v188
	ds_bpermute_b32 v189, v216, v189
	ds_bpermute_b32 v190, v216, v190
	ds_bpermute_b32 v191, v216, v191
	ds_bpermute_b32 v192, v216, v192
	ds_bpermute_b32 v193, v216, v193
	ds_bpermute_b32 v194, v216, v194
	ds_bpermute_b32 v195, v216, v195
	ds_bpermute_b32 v196, v216, v196
	ds_bpermute_b32 v197, v216, v197
	ds_bpermute_b32 v198, v216, v198
	ds_bpermute_b32 v199, v216, v199
	s_waitcnt lgkmcnt(0)
	v_mfma_f32_16x16x32_bf16 v[44:47], v[76:79], v[188:191], v[44:47]
	v_mfma_f32_16x16x32_bf16 v[44:47], v[96:99], v[192:195], v[44:47]
	v_mfma_f32_16x16x32_bf16 v[44:47], v[100:103], v[196:199], v[44:47]
.Lsk273_b0_mm7:
	s_and_b64 vcc, exec, s[70:71]
	s_cbranch_vccz .Lsk273_b0_mm8
	ds_bpermute_b32 v200, v216, v200
	ds_bpermute_b32 v201, v216, v201
	ds_bpermute_b32 v202, v216, v202
	ds_bpermute_b32 v203, v216, v203
	ds_bpermute_b32 v204, v216, v204
	ds_bpermute_b32 v205, v216, v205
	ds_bpermute_b32 v206, v216, v206
	ds_bpermute_b32 v207, v216, v207
	ds_bpermute_b32 v208, v216, v208
	ds_bpermute_b32 v209, v216, v209
	ds_bpermute_b32 v210, v216, v210
	ds_bpermute_b32 v211, v216, v211
	s_waitcnt lgkmcnt(0)
	v_mfma_f32_16x16x32_bf16 v[40:43], v[76:79], v[200:203], v[40:43]
	v_mfma_f32_16x16x32_bf16 v[40:43], v[96:99], v[204:207], v[40:43]
	v_mfma_f32_16x16x32_bf16 v[40:43], v[100:103], v[208:211], v[40:43]
.Lsk273_b0_mm8:
	s_mov_b64 s[6:7], 0x600
	v_lshl_add_u64 v[218:219], v[218:219], 0, s[6:7]
	v_lshl_add_u64 v[214:215], v[214:215], 0, s[6:7]
	global_load_dwordx4 v[76:79], v[218:219], off
	s_and_b64 vcc, exec, s[28:29]
	s_cbranch_vccz .Lsk273_b1_ld0
	global_load_dwordx4 v[104:107], v[214:215], off
.Lsk273_b1_ld0:
	v_lshl_add_u64 v[228:229], v[214:215], 0, s[8:9]
	s_and_b64 vcc, exec, s[30:31]
	s_cbranch_vccz .Lsk273_b1_ld1
	global_load_dwordx4 v[116:119], v[228:229], off
.Lsk273_b1_ld1:
	v_lshl_add_u64 v[230:231], v[228:229], 0, s[8:9]
	s_and_b64 vcc, exec, s[80:81]
	s_cbranch_vccz .Lsk273_b1_ld2
	global_load_dwordx4 v[128:131], v[230:231], off
.Lsk273_b1_ld2:
	v_lshl_add_u64 v[228:229], v[230:231], 0, s[8:9]
	s_and_b64 vcc, exec, s[82:83]
	s_cbranch_vccz .Lsk273_b1_ld3
	global_load_dwordx4 v[140:143], v[228:229], off
.Lsk273_b1_ld3:
	v_lshl_add_u64 v[230:231], v[228:229], 0, s[8:9]
	s_and_b64 vcc, exec, s[84:85]
	s_cbranch_vccz .Lsk273_b1_ld4
	global_load_dwordx4 v[152:155], v[230:231], off
.Lsk273_b1_ld4:
	v_lshl_add_u64 v[228:229], v[230:231], 0, s[8:9]
	s_and_b64 vcc, exec, s[86:87]
	s_cbranch_vccz .Lsk273_b1_ld5
	global_load_dwordx4 v[164:167], v[228:229], off
.Lsk273_b1_ld5:
	v_lshl_add_u64 v[230:231], v[228:229], 0, s[8:9]
	s_and_b64 vcc, exec, s[88:89]
	s_cbranch_vccz .Lsk273_b1_ld6
	global_load_dwordx4 v[176:179], v[230:231], off
.Lsk273_b1_ld6:
	v_lshl_add_u64 v[228:229], v[230:231], 0, s[8:9]
	s_and_b64 vcc, exec, s[90:91]
	s_cbranch_vccz .Lsk273_b1_ld7
	global_load_dwordx4 v[188:191], v[228:229], off
.Lsk273_b1_ld7:
	v_lshl_add_u64 v[230:231], v[228:229], 0, s[8:9]
	s_and_b64 vcc, exec, s[70:71]
	s_cbranch_vccz .Lsk273_b1_ld8
	global_load_dwordx4 v[200:203], v[230:231], off
.Lsk273_b1_ld8:
	s_waitcnt vmcnt(0)
	ds_bpermute_b32 v76, v216, v76
	ds_bpermute_b32 v77, v216, v77
	ds_bpermute_b32 v78, v216, v78
	ds_bpermute_b32 v79, v216, v79
	s_and_b64 vcc, exec, s[28:29]
	s_cbranch_vccz .Lsk273_b1_mm0
	ds_bpermute_b32 v104, v216, v104
	ds_bpermute_b32 v105, v216, v105
	ds_bpermute_b32 v106, v216, v106
	ds_bpermute_b32 v107, v216, v107
	s_waitcnt lgkmcnt(0)
	v_mfma_f32_16x16x32_bf16 v[72:75], v[76:79], v[104:107], v[72:75]
.Lsk273_b1_mm0:
	s_and_b64 vcc, exec, s[30:31]
	s_cbranch_vccz .Lsk273_b1_mm1
	ds_bpermute_b32 v116, v216, v116
	ds_bpermute_b32 v117, v216, v117
	ds_bpermute_b32 v118, v216, v118
	ds_bpermute_b32 v119, v216, v119
	s_waitcnt lgkmcnt(0)
	v_mfma_f32_16x16x32_bf16 v[68:71], v[76:79], v[116:119], v[68:71]
.Lsk273_b1_mm1:
	s_and_b64 vcc, exec, s[80:81]
	s_cbranch_vccz .Lsk273_b1_mm2
	ds_bpermute_b32 v128, v216, v128
	ds_bpermute_b32 v129, v216, v129
	ds_bpermute_b32 v130, v216, v130
	ds_bpermute_b32 v131, v216, v131
	s_waitcnt lgkmcnt(0)
	v_mfma_f32_16x16x32_bf16 v[64:67], v[76:79], v[128:131], v[64:67]
.Lsk273_b1_mm2:
	s_and_b64 vcc, exec, s[82:83]
	s_cbranch_vccz .Lsk273_b1_mm3
	ds_bpermute_b32 v140, v216, v140
	ds_bpermute_b32 v141, v216, v141
	ds_bpermute_b32 v142, v216, v142
	ds_bpermute_b32 v143, v216, v143
	s_waitcnt lgkmcnt(0)
	v_mfma_f32_16x16x32_bf16 v[60:63], v[76:79], v[140:143], v[60:63]
.Lsk273_b1_mm3:
	s_and_b64 vcc, exec, s[84:85]
	s_cbranch_vccz .Lsk273_b1_mm4
	ds_bpermute_b32 v152, v216, v152
	ds_bpermute_b32 v153, v216, v153
	ds_bpermute_b32 v154, v216, v154
	ds_bpermute_b32 v155, v216, v155
	s_waitcnt lgkmcnt(0)
	v_mfma_f32_16x16x32_bf16 v[56:59], v[76:79], v[152:155], v[56:59]
.Lsk273_b1_mm4:
	s_and_b64 vcc, exec, s[86:87]
	s_cbranch_vccz .Lsk273_b1_mm5
	ds_bpermute_b32 v164, v216, v164
	ds_bpermute_b32 v165, v216, v165
	ds_bpermute_b32 v166, v216, v166
	ds_bpermute_b32 v167, v216, v167
	s_waitcnt lgkmcnt(0)
	v_mfma_f32_16x16x32_bf16 v[52:55], v[76:79], v[164:167], v[52:55]
.Lsk273_b1_mm5:
	s_and_b64 vcc, exec, s[88:89]
	s_cbranch_vccz .Lsk273_b1_mm6
	ds_bpermute_b32 v176, v216, v176
	ds_bpermute_b32 v177, v216, v177
	ds_bpermute_b32 v178, v216, v178
	ds_bpermute_b32 v179, v216, v179
	s_waitcnt lgkmcnt(0)
	v_mfma_f32_16x16x32_bf16 v[48:51], v[76:79], v[176:179], v[48:51]
.Lsk273_b1_mm6:
	s_and_b64 vcc, exec, s[90:91]
	s_cbranch_vccz .Lsk273_b1_mm7
	ds_bpermute_b32 v188, v216, v188
	ds_bpermute_b32 v189, v216, v189
	ds_bpermute_b32 v190, v216, v190
	ds_bpermute_b32 v191, v216, v191
	s_waitcnt lgkmcnt(0)
	v_mfma_f32_16x16x32_bf16 v[44:47], v[76:79], v[188:191], v[44:47]
.Lsk273_b1_mm7:
	s_and_b64 vcc, exec, s[70:71]
	s_cbranch_vccz .Lsk273_b1_mm8
	ds_bpermute_b32 v200, v216, v200
	ds_bpermute_b32 v201, v216, v201
	ds_bpermute_b32 v202, v216, v202
	ds_bpermute_b32 v203, v216, v203
	s_waitcnt lgkmcnt(0)
	v_mfma_f32_16x16x32_bf16 v[40:43], v[76:79], v[200:203], v[40:43]
.Lsk273_b1_mm8:
	s_branch .LBB0_310
.LBB0_309:
	v_mov_b32_e32 v74, v75
	v_mov_b32_e32 v73, v75
	v_mov_b32_e32 v72, v75
	v_mov_b32_e32 v71, v75
	v_mov_b32_e32 v70, v75
	v_mov_b32_e32 v69, v75
	v_mov_b32_e32 v68, v75
	v_mov_b32_e32 v67, v75
	v_mov_b32_e32 v66, v75
	v_mov_b32_e32 v65, v75
	v_mov_b32_e32 v64, v75
	v_mov_b32_e32 v63, v75
	v_mov_b32_e32 v62, v75
	v_mov_b32_e32 v61, v75
	v_mov_b32_e32 v60, v75
	v_mov_b32_e32 v59, v75
	v_mov_b32_e32 v58, v75
	v_mov_b32_e32 v57, v75
	v_mov_b32_e32 v56, v75
	v_mov_b32_e32 v55, v75
	v_mov_b32_e32 v54, v75
	v_mov_b32_e32 v53, v75
	v_mov_b32_e32 v52, v75
	v_mov_b32_e32 v51, v75
	v_mov_b32_e32 v50, v75
	v_mov_b32_e32 v49, v75
	v_mov_b32_e32 v48, v75
	v_mov_b32_e32 v47, v75
	v_mov_b32_e32 v46, v75
	v_mov_b32_e32 v45, v75
	v_mov_b32_e32 v44, v75
	v_mov_b32_e32 v43, v75
	v_mov_b32_e32 v42, v75
	v_mov_b32_e32 v41, v75
	v_mov_b32_e32 v40, v75
	s_branch .LBB0_311

.LBB0_1080:
	v_mbcnt_lo_u32_b32 v212, -1, 0
	v_mbcnt_hi_u32_b32 v212, -1, v212
	v_lshrrev_b32_e32 v214, 2, v212
	v_and_b32_e32 v215, 15, v212
	v_sub_u32_e32 v214, v214, v215
	v_mul_i32_i24_e32 v214, 0x800, v214
	v_lshlrev_b32_e32 v216, 4, v215
	v_and_b32_e32 v215, 3, v212
	v_lshrrev_b32_e32 v212, 4, v212
	v_sub_u32_e32 v215, v215, v212
	v_lshl_add_u32 v214, v215, 4, v214
	v_lshl_add_u32 v216, v212, 2, v216
	v_ashrrev_i32_e32 v215, 31, v214
	s_lshl_b32 s4, s70, 1
	s_mov_b32 s5, 0
	v_lshl_add_u64 v[218:219], v[82:83], 0, v[214:215]
	v_lshl_add_u64 v[214:215], v[80:81], 0, v[214:215]
	v_lshl_add_u64 v[218:219], v[218:219], 0, s[4:5]
	v_lshl_add_u64 v[214:215], v[214:215], 0, s[4:5]
	s_mov_b64 s[6:7], 0x8000
	global_load_dwordx4 v[76:79], v[218:219], off
	global_load_dwordx4 v[96:99], v[218:219], off offset:512
	global_load_dwordx4 v[100:103], v[218:219], off offset:1024
	s_and_b64 vcc, exec, s[28:29]
	s_cbranch_vccz .Lsk1080_b0_ld0
	global_load_dwordx4 v[104:107], v[214:215], off
	global_load_dwordx4 v[108:111], v[214:215], off offset:512
	global_load_dwordx4 v[112:115], v[214:215], off offset:1024
.Lsk1080_b0_ld0:
	v_lshl_add_u64 v[228:229], v[214:215], 0, s[6:7]
	s_and_b64 vcc, exec, s[30:31]
	s_cbranch_vccz .Lsk1080_b0_ld1
	global_load_dwordx4 v[116:119], v[228:229], off
	global_load_dwordx4 v[120:123], v[228:229], off offset:512
	global_load_dwordx4 v[124:127], v[228:229], off offset:1024
.Lsk1080_b0_ld1:
	v_lshl_add_u64 v[230:231], v[228:229], 0, s[6:7]
	s_and_b64 vcc, exec, s[44:45]
	s_cbranch_vccz .Lsk1080_b0_ld2
	global_load_dwordx4 v[128:131], v[230:231], off
	global_load_dwordx4 v[132:135], v[230:231], off offset:512
	global_load_dwordx4 v[136:139], v[230:231], off offset:1024
.Lsk1080_b0_ld2:
	v_lshl_add_u64 v[228:229], v[230:231], 0, s[6:7]
	s_and_b64 vcc, exec, s[46:47]
	s_cbranch_vccz .Lsk1080_b0_ld3
	global_load_dwordx4 v[140:143], v[228:229], off
	global_load_dwordx4 v[144:147], v[228:229], off offset:512
	global_load_dwordx4 v[148:151], v[228:229], off offset:1024
.Lsk1080_b0_ld3:
	v_lshl_add_u64 v[230:231], v[228:229], 0, s[6:7]
	s_and_b64 vcc, exec, s[52:53]
	s_cbranch_vccz .Lsk1080_b0_ld4
	global_load_dwordx4 v[152:155], v[230:231], off
	global_load_dwordx4 v[156:159], v[230:231], off offset:512
	global_load_dwordx4 v[160:163], v[230:231], off offset:1024
.Lsk1080_b0_ld4:
	v_lshl_add_u64 v[228:229], v[230:231], 0, s[6:7]
	s_and_b64 vcc, exec, s[56:57]
	s_cbranch_vccz .Lsk1080_b0_ld5
	global_load_dwordx4 v[164:167], v[228:229], off
	global_load_dwordx4 v[168:171], v[228:229], off offset:512
	global_load_dwordx4 v[172:175], v[228:229], off offset:1024
.Lsk1080_b0_ld5:
	v_lshl_add_u64 v[230:231], v[228:229], 0, s[6:7]
	s_and_b64 vcc, exec, s[66:67]
	s_cbranch_vccz .Lsk1080_b0_ld6
	global_load_dwordx4 v[176:179], v[230:231], off
	global_load_dwordx4 v[180:183], v[230:231], off offset:512
	global_load_dwordx4 v[184:187], v[230:231], off offset:1024
.Lsk1080_b0_ld6:
	v_lshl_add_u64 v[228:229], v[230:231], 0, s[6:7]
	s_and_b64 vcc, exec, s[2:3]
	s_cbranch_vccz .Lsk1080_b0_ld7
	global_load_dwordx4 v[188:191], v[228:229], off
	global_load_dwordx4 v[192:195], v[228:229], off offset:512
	global_load_dwordx4 v[196:199], v[228:229], off offset:1024
.Lsk1080_b0_ld7:
	v_lshl_add_u64 v[230:231], v[228:229], 0, s[6:7]
	s_and_b64 vcc, exec, s[0:1]
	s_cbranch_vccz .Lsk1080_b0_ld8
	global_load_dwordx4 v[200:203], v[230:231], off
	global_load_dwordx4 v[204:207], v[230:231], off offset:512
	global_load_dwordx4 v[208:211], v[230:231], off offset:1024

.Lsk1080_b0_mm1:
	s_and_b64 vcc, exec, s[44:45]
	s_cbranch_vccz .Lsk1080_b0_mm2
	ds_bpermute_b32 v128, v216, v128
	ds_bpermute_b32 v129, v216, v129
	ds_bpermute_b32 v130, v216, v130
	ds_bpermute_b32 v131, v216, v131
	ds_bpermute_b32 v132, v216, v132
	ds_bpermute_b32 v133, v216, v133
	ds_bpermute_b32 v134, v216, v134
	ds_bpermute_b32 v135, v216, v135
	ds_bpermute_b32 v136, v216, v136
	ds_bpermute_b32 v137, v216, v137
	ds_bpermute_b32 v138, v216, v138
	ds_bpermute_b32 v139, v216, v139
	s_waitcnt lgkmcnt(0)
	v_mfma_f32_16x16x32_bf16 v[64:67], v[76:79], v[128:131], v[64:67]
	v_mfma_f32_16x16x32_bf16 v[64:67], v[96:99], v[132:135], v[64:67]
	v_mfma_f32_16x16x32_bf16 v[64:67], v[100:103], v[136:139], v[64:67]
.Lsk1080_b0_mm2:
	s_and_b64 vcc, exec, s[46:47]
	s_cbranch_vccz .Lsk1080_b0_mm3
	ds_bpermute_b32 v140, v216, v140
	ds_bpermute_b32 v141, v216, v141
	ds_bpermute_b32 v142, v216, v142
	ds_bpermute_b32 v143, v216, v143
	ds_bpermute_b32 v144, v216, v144
	ds_bpermute_b32 v145, v216, v145
	ds_bpermute_b32 v146, v216, v146
	ds_bpermute_b32 v147, v216, v147
	ds_bpermute_b32 v148, v216, v148
	ds_bpermute_b32 v149, v216, v149
	ds_bpermute_b32 v150, v216, v150
	ds_bpermute_b32 v151, v216, v151
	s_waitcnt lgkmcnt(0)
	v_mfma_f32_16x16x32_bf16 v[60:63], v[76:79], v[140:143], v[60:63]
	v_mfma_f32_16x16x32_bf16 v[60:63], v[96:99], v[144:147], v[60:63]
	v_mfma_f32_16x16x32_bf16 v[60:63], v[100:103], v[148:151], v[60:63]
.Lsk1080_b0_mm3:
	s_and_b64 vcc, exec, s[52:53]
	s_cbranch_vccz .Lsk1080_b0_mm4
	ds_bpermute_b32 v152, v216, v152
	ds_bpermute_b32 v153, v216, v153
	ds_bpermute_b32 v154, v216, v154
	ds_bpermute_b32 v155, v216, v155
	ds_bpermute_b32 v156, v216, v156
	ds_bpermute_b32 v157, v216, v157
	ds_bpermute_b32 v158, v216, v158
	ds_bpermute_b32 v159, v216, v159
	ds_bpermute_b32 v160, v216, v160
	ds_bpermute_b32 v161, v216, v161
	ds_bpermute_b32 v162, v216, v162
	ds_bpermute_b32 v163, v216, v163
	s_waitcnt lgkmcnt(0)
	v_mfma_f32_16x16x32_bf16 v[56:59], v[76:79], v[152:155], v[56:59]
	v_mfma_f32_16x16x32_bf16 v[56:59], v[96:99], v[156:159], v[56:59]
	v_mfma_f32_16x16x32_bf16 v[56:59], v[100:103], v[160:163], v[56:59]
.Lsk1080_b0_mm4:
	s_and_b64 vcc, exec, s[56:57]
	s_cbranch_vccz .Lsk1080_b0_mm5
	ds_bpermute_b32 v164, v216, v164
	ds_bpermute_b32 v165, v216, v165
	ds_bpermute_b32 v166, v216, v166
	ds_bpermute_b32 v167, v216, v167
	ds_bpermute_b32 v168, v216, v168
	ds_bpermute_b32 v169, v216, v169
	ds_bpermute_b32 v170, v216, v170
	ds_bpermute_b32 v171, v216, v171
	ds_bpermute_b32 v172, v216, v172
	ds_bpermute_b32 v173, v216, v173
	ds_bpermute_b32 v174, v216, v174
	ds_bpermute_b32 v175, v216, v175
	s_waitcnt lgkmcnt(0)
	v_mfma_f32_16x16x32_bf16 v[52:55], v[76:79], v[164:167], v[52:55]
	v_mfma_f32_16x16x32_bf16 v[52:55], v[96:99], v[168:171], v[52:55]
	v_mfma_f32_16x16x32_bf16 v[52:55], v[100:103], v[172:175], v[52:55]
.Lsk1080_b0_mm5:
	s_and_b64 vcc, exec, s[66:67]
	s_cbranch_vccz .Lsk1080_b0_mm6
	ds_bpermute_b32 v176, v216, v176
	ds_bpermute_b32 v177, v216, v177
	ds_bpermute_b32 v178, v216, v178
	ds_bpermute_b32 v179, v216, v179
	ds_bpermute_b32 v180, v216, v180
	ds_bpermute_b32 v181, v216, v181
	ds_bpermute_b32 v182, v216, v182
	ds_bpermute_b32 v183, v216, v183
	ds_bpermute_b32 v184, v216, v184
	ds_bpermute_b32 v185, v216, v185
	ds_bpermute_b32 v186, v216, v186
	ds_bpermute_b32 v187, v216, v187
	s_waitcnt lgkmcnt(0)
	v_mfma_f32_16x16x32_bf16 v[48:51], v[76:79], v[176:179], v[48:51]
	v_mfma_f32_16x16x32_bf16 v[48:51], v[96:99], v[180:183], v[48:51]
	v_mfma_f32_16x16x32_bf16 v[48:51], v[100:103], v[184:187], v[48:51]
.Lsk1080_b0_mm6:
	s_and_b64 vcc, exec, s[2:3]
	s_cbranch_vccz .Lsk1080_b0_mm7
	ds_bpermute_b32 v188, v216, v188
	ds_bpermute_b32 v189, v216, v189
	ds_bpermute_b32 v190, v216, v190
	ds_bpermute_b32 v191, v216, v191
	ds_bpermute_b32 v192, v216, v192
	ds_bpermute_b32 v193, v216, v193
	ds_bpermute_b32 v194, v216, v194
	ds_bpermute_b32 v195, v216, v195
	ds_bpermute_b32 v196, v216, v196
	ds_bpermute_b32 v197, v216, v197
	ds_bpermute_b32 v198, v216, v198
	ds_bpermute_b32 v199, v216, v199
	s_waitcnt lgkmcnt(0)
	v_mfma_f32_16x16x32_bf16 v[44:47], v[76:79], v[188:191], v[44:47]
	v_mfma_f32_16x16x32_bf16 v[44:47], v[96:99], v[192:195], v[44:47]
	v_mfma_f32_16x16x32_bf16 v[44:47], v[100:103], v[196:199], v[44:47]
.Lsk1080_b0_mm7:
	s_and_b64 vcc, exec, s[0:1]
	s_cbranch_vccz .Lsk1080_b0_mm8
	ds_bpermute_b32 v200, v216, v200
	ds_bpermute_b32 v201, v216, v201
	ds_bpermute_b32 v202, v216, v202
	ds_bpermute_b32 v203, v216, v203
	ds_bpermute_b32 v204, v216, v204
	ds_bpermute_b32 v205, v216, v205
	ds_bpermute_b32 v206, v216, v206
	ds_bpermute_b32 v207, v216, v207
	ds_bpermute_b32 v208, v216, v208
	ds_bpermute_b32 v209, v216, v209
	ds_bpermute_b32 v210, v216, v210
	ds_bpermute_b32 v211, v216, v211
	s_waitcnt lgkmcnt(0)
	v_mfma_f32_16x16x32_bf16 v[40:43], v[76:79], v[200:203], v[40:43]
	v_mfma_f32_16x16x32_bf16 v[40:43], v[96:99], v[204:207], v[40:43]
	v_mfma_f32_16x16x32_bf16 v[40:43], v[100:103], v[208:211], v[40:43]
.Lsk1080_b0_mm8:
	s_mov_b64 s[4:5], 0x600
	v_lshl_add_u64 v[218:219], v[218:219], 0, s[4:5]
	v_lshl_add_u64 v[214:215], v[214:215], 0, s[4:5]
	global_load_dwordx4 v[76:79], v[218:219], off
	s_and_b64 vcc, exec, s[28:29]
	s_cbranch_vccz .Lsk1080_b1_ld0
	global_load_dwordx4 v[104:107], v[214:215], off
.Lsk1080_b1_ld0:
	v_lshl_add_u64 v[228:229], v[214:215], 0, s[6:7]
	s_and_b64 vcc, exec, s[30:31]
	s_cbranch_vccz .Lsk1080_b1_ld1
	global_load_dwordx4 v[116:119], v[228:229], off
.Lsk1080_b1_ld1:
	v_lshl_add_u64 v[230:231], v[228:229], 0, s[6:7]
	s_and_b64 vcc, exec, s[44:45]
	s_cbranch_vccz .Lsk1080_b1_ld2
	global_load_dwordx4 v[128:131], v[230:231], off
.Lsk1080_b1_ld2:
	v_lshl_add_u64 v[228:229], v[230:231], 0, s[6:7]
	s_and_b64 vcc, exec, s[46:47]
	s_cbranch_vccz .Lsk1080_b1_ld3
	global_load_dwordx4 v[140:143], v[228:229], off
.Lsk1080_b1_ld3:
	v_lshl_add_u64 v[230:231], v[228:229], 0, s[6:7]
	s_and_b64 vcc, exec, s[52:53]
	s_cbranch_vccz .Lsk1080_b1_ld4
	global_load_dwordx4 v[152:155], v[230:231], off
.Lsk1080_b1_ld4:
	v_lshl_add_u64 v[228:229], v[230:231], 0, s[6:7]
	s_and_b64 vcc, exec, s[56:57]
	s_cbranch_vccz .Lsk1080_b1_ld5
	global_load_dwordx4 v[164:167], v[228:229], off
.Lsk1080_b1_ld5:
	v_lshl_add_u64 v[230:231], v[228:229], 0, s[6:7]
	s_and_b64 vcc, exec, s[66:67]
	s_cbranch_vccz .Lsk1080_b1_ld6
	global_load_dwordx4 v[176:179], v[230:231], off
.Lsk1080_b1_ld6:
	v_lshl_add_u64 v[228:229], v[230:231], 0, s[6:7]
	s_and_b64 vcc, exec, s[2:3]
	s_cbranch_vccz .Lsk1080_b1_ld7
	global_load_dwordx4 v[188:191], v[228:229], off
.Lsk1080_b1_ld7:
	v_lshl_add_u64 v[230:231], v[228:229], 0, s[6:7]
	s_and_b64 vcc, exec, s[0:1]
	s_cbranch_vccz .Lsk1080_b1_ld8
	global_load_dwordx4 v[200:203], v[230:231], off

.Lsk1080_b1_mm1:
	s_and_b64 vcc, exec, s[44:45]
	s_cbranch_vccz .Lsk1080_b1_mm2
	ds_bpermute_b32 v128, v216, v128
	ds_bpermute_b32 v129, v216, v129
	ds_bpermute_b32 v130, v216, v130
	ds_bpermute_b32 v131, v216, v131
	s_waitcnt lgkmcnt(0)
	v_mfma_f32_16x16x32_bf16 v[64:67], v[76:79], v[128:131], v[64:67]
.Lsk1080_b1_mm2:
	s_and_b64 vcc, exec, s[46:47]
	s_cbranch_vccz .Lsk1080_b1_mm3
	ds_bpermute_b32 v140, v216, v140
	ds_bpermute_b32 v141, v216, v141
	ds_bpermute_b32 v142, v216, v142
	ds_bpermute_b32 v143, v216, v143
	s_waitcnt lgkmcnt(0)
	v_mfma_f32_16x16x32_bf16 v[60:63], v[76:79], v[140:143], v[60:63]
.Lsk1080_b1_mm3:
	s_and_b64 vcc, exec, s[52:53]
	s_cbranch_vccz .Lsk1080_b1_mm4
	ds_bpermute_b32 v152, v216, v152
	ds_bpermute_b32 v153, v216, v153
	ds_bpermute_b32 v154, v216, v154
	ds_bpermute_b32 v155, v216, v155
	s_waitcnt lgkmcnt(0)
	v_mfma_f32_16x16x32_bf16 v[56:59], v[76:79], v[152:155], v[56:59]
.Lsk1080_b1_mm4:
	s_and_b64 vcc, exec, s[56:57]
	s_cbranch_vccz .Lsk1080_b1_mm5
	ds_bpermute_b32 v164, v216, v164
	ds_bpermute_b32 v165, v216, v165
	ds_bpermute_b32 v166, v216, v166
	ds_bpermute_b32 v167, v216, v167
	s_waitcnt lgkmcnt(0)
	v_mfma_f32_16x16x32_bf16 v[52:55], v[76:79], v[164:167], v[52:55]
.Lsk1080_b1_mm5:
	s_and_b64 vcc, exec, s[66:67]
	s_cbranch_vccz .Lsk1080_b1_mm6
	ds_bpermute_b32 v176, v216, v176
	ds_bpermute_b32 v177, v216, v177
	ds_bpermute_b32 v178, v216, v178
	ds_bpermute_b32 v179, v216, v179
	s_waitcnt lgkmcnt(0)
	v_mfma_f32_16x16x32_bf16 v[48:51], v[76:79], v[176:179], v[48:51]
.Lsk1080_b1_mm6:
	s_and_b64 vcc, exec, s[2:3]
	s_cbranch_vccz .Lsk1080_b1_mm7
	ds_bpermute_b32 v188, v216, v188
	ds_bpermute_b32 v189, v216, v189
	ds_bpermute_b32 v190, v216, v190
	ds_bpermute_b32 v191, v216, v191
	s_waitcnt lgkmcnt(0)
	v_mfma_f32_16x16x32_bf16 v[44:47], v[76:79], v[188:191], v[44:47]
.Lsk1080_b1_mm7:
	s_and_b64 vcc, exec, s[0:1]
	s_cbranch_vccz .Lsk1080_b1_mm8
	ds_bpermute_b32 v200, v216, v200
	ds_bpermute_b32 v201, v216, v201
	ds_bpermute_b32 v202, v216, v202
	ds_bpermute_b32 v203, v216, v203
	s_waitcnt lgkmcnt(0)
	v_mfma_f32_16x16x32_bf16 v[40:43], v[76:79], v[200:203], v[40:43]
.Lsk1080_b1_mm8:
	s_branch .LBB0_1117
.LBB0_1116:
	v_mov_b32_e32 v74, v75
	v_mov_b32_e32 v73, v75
	v_mov_b32_e32 v72, v75
	s_waitcnt vmcnt(0)
	v_mov_b32_e32 v71, v75
	v_mov_b32_e32 v70, v75
	v_mov_b32_e32 v69, v75
	v_mov_b32_e32 v68, v75
	v_mov_b32_e32 v67, v75
	v_mov_b32_e32 v66, v75
	v_mov_b32_e32 v65, v75
	v_mov_b32_e32 v64, v75
	v_mov_b32_e32 v63, v75
	v_mov_b32_e32 v62, v75
	v_mov_b32_e32 v61, v75
	v_mov_b32_e32 v60, v75
	v_mov_b32_e32 v59, v75
	v_mov_b32_e32 v58, v75
	v_mov_b32_e32 v57, v75
	v_mov_b32_e32 v56, v75
	v_mov_b32_e32 v55, v75
	v_mov_b32_e32 v54, v75
	v_mov_b32_e32 v53, v75
	v_mov_b32_e32 v52, v75
	v_mov_b32_e32 v51, v75
	v_mov_b32_e32 v50, v75
	v_mov_b32_e32 v49, v75
	v_mov_b32_e32 v48, v75
	v_mov_b32_e32 v47, v75
	v_mov_b32_e32 v46, v75
	v_mov_b32_e32 v45, v75
	v_mov_b32_e32 v44, v75
	v_mov_b32_e32 v43, v75
	v_mov_b32_e32 v42, v75
	v_mov_b32_e32 v41, v75
	v_mov_b32_e32 v40, v75
	s_branch .LBB0_1118

.LBB0_1891:
	v_mbcnt_lo_u32_b32 v212, -1, 0
	v_mbcnt_hi_u32_b32 v212, -1, v212
	v_lshrrev_b32_e32 v214, 2, v212
	v_and_b32_e32 v215, 15, v212
	v_sub_u32_e32 v214, v214, v215
	v_mul_i32_i24_e32 v214, 0x800, v214
	v_lshlrev_b32_e32 v216, 4, v215
	v_and_b32_e32 v215, 3, v212
	v_lshrrev_b32_e32 v212, 4, v212
	v_sub_u32_e32 v215, v215, v212
	v_lshl_add_u32 v214, v215, 4, v214
	v_lshl_add_u32 v216, v212, 2, v216
	v_ashrrev_i32_e32 v215, 31, v214
	s_lshl_b32 s6, s2, 1
	s_mov_b32 s7, 0
	v_lshl_add_u64 v[218:219], v[82:83], 0, v[214:215]
	v_lshl_add_u64 v[214:215], v[80:81], 0, v[214:215]
	v_lshl_add_u64 v[218:219], v[218:219], 0, s[6:7]
	v_lshl_add_u64 v[214:215], v[214:215], 0, s[6:7]
	s_mov_b64 s[8:9], 0x8000
	global_load_dwordx4 v[76:79], v[218:219], off
	global_load_dwordx4 v[96:99], v[218:219], off offset:512
	global_load_dwordx4 v[100:103], v[218:219], off offset:1024
	s_and_b64 vcc, exec, s[28:29]
	s_cbranch_vccz .Lsk1891_b0_ld0
	global_load_dwordx4 v[104:107], v[214:215], off
	global_load_dwordx4 v[108:111], v[214:215], off offset:512
	global_load_dwordx4 v[112:115], v[214:215], off offset:1024

.Lsk1891_b0_ld1:
	v_lshl_add_u64 v[230:231], v[228:229], 0, s[8:9]
	s_and_b64 vcc, exec, s[76:77]
	s_cbranch_vccz .Lsk1891_b0_ld2
	global_load_dwordx4 v[128:131], v[230:231], off
	global_load_dwordx4 v[132:135], v[230:231], off offset:512
	global_load_dwordx4 v[136:139], v[230:231], off offset:1024
.Lsk1891_b0_ld2:
	v_lshl_add_u64 v[228:229], v[230:231], 0, s[8:9]
	s_and_b64 vcc, exec, s[78:79]
	s_cbranch_vccz .Lsk1891_b0_ld3
	global_load_dwordx4 v[140:143], v[228:229], off
	global_load_dwordx4 v[144:147], v[228:229], off offset:512
	global_load_dwordx4 v[148:151], v[228:229], off offset:1024
.Lsk1891_b0_ld3:
	v_lshl_add_u64 v[230:231], v[228:229], 0, s[8:9]
	s_and_b64 vcc, exec, s[80:81]
	s_cbranch_vccz .Lsk1891_b0_ld4
	global_load_dwordx4 v[152:155], v[230:231], off
	global_load_dwordx4 v[156:159], v[230:231], off offset:512
	global_load_dwordx4 v[160:163], v[230:231], off offset:1024
.Lsk1891_b0_ld4:
	v_lshl_add_u64 v[228:229], v[230:231], 0, s[8:9]
	s_and_b64 vcc, exec, s[82:83]
	s_cbranch_vccz .Lsk1891_b0_ld5
	global_load_dwordx4 v[164:167], v[228:229], off
	global_load_dwordx4 v[168:171], v[228:229], off offset:512
	global_load_dwordx4 v[172:175], v[228:229], off offset:1024
.Lsk1891_b0_ld5:
	v_lshl_add_u64 v[230:231], v[228:229], 0, s[8:9]
	s_and_b64 vcc, exec, s[84:85]
	s_cbranch_vccz .Lsk1891_b0_ld6
	global_load_dwordx4 v[176:179], v[230:231], off
	global_load_dwordx4 v[180:183], v[230:231], off offset:512
	global_load_dwordx4 v[184:187], v[230:231], off offset:1024
.Lsk1891_b0_ld6:
	v_lshl_add_u64 v[228:229], v[230:231], 0, s[8:9]
	s_and_b64 vcc, exec, s[86:87]
	s_cbranch_vccz .Lsk1891_b0_ld7
	global_load_dwordx4 v[188:191], v[228:229], off
	global_load_dwordx4 v[192:195], v[228:229], off offset:512
	global_load_dwordx4 v[196:199], v[228:229], off offset:1024

.Lsk1891_b0_mm1:
	s_and_b64 vcc, exec, s[76:77]
	s_cbranch_vccz .Lsk1891_b0_mm2
	ds_bpermute_b32 v128, v216, v128
	ds_bpermute_b32 v129, v216, v129
	ds_bpermute_b32 v130, v216, v130
	ds_bpermute_b32 v131, v216, v131
	ds_bpermute_b32 v132, v216, v132
	ds_bpermute_b32 v133, v216, v133
	ds_bpermute_b32 v134, v216, v134
	ds_bpermute_b32 v135, v216, v135
	ds_bpermute_b32 v136, v216, v136
	ds_bpermute_b32 v137, v216, v137
	ds_bpermute_b32 v138, v216, v138
	ds_bpermute_b32 v139, v216, v139
	s_waitcnt lgkmcnt(0)
	v_mfma_f32_16x16x32_bf16 v[64:67], v[76:79], v[128:131], v[64:67]
	v_mfma_f32_16x16x32_bf16 v[64:67], v[96:99], v[132:135], v[64:67]
	v_mfma_f32_16x16x32_bf16 v[64:67], v[100:103], v[136:139], v[64:67]
.Lsk1891_b0_mm2:
	s_and_b64 vcc, exec, s[78:79]
	s_cbranch_vccz .Lsk1891_b0_mm3
	ds_bpermute_b32 v140, v216, v140
	ds_bpermute_b32 v141, v216, v141
	ds_bpermute_b32 v142, v216, v142
	ds_bpermute_b32 v143, v216, v143
	ds_bpermute_b32 v144, v216, v144
	ds_bpermute_b32 v145, v216, v145
	ds_bpermute_b32 v146, v216, v146
	ds_bpermute_b32 v147, v216, v147
	ds_bpermute_b32 v148, v216, v148
	ds_bpermute_b32 v149, v216, v149
	ds_bpermute_b32 v150, v216, v150
	ds_bpermute_b32 v151, v216, v151
	s_waitcnt lgkmcnt(0)
	v_mfma_f32_16x16x32_bf16 v[60:63], v[76:79], v[140:143], v[60:63]
	v_mfma_f32_16x16x32_bf16 v[60:63], v[96:99], v[144:147], v[60:63]
	v_mfma_f32_16x16x32_bf16 v[60:63], v[100:103], v[148:151], v[60:63]
.Lsk1891_b0_mm3:
	s_and_b64 vcc, exec, s[80:81]
	s_cbranch_vccz .Lsk1891_b0_mm4
	ds_bpermute_b32 v152, v216, v152
	ds_bpermute_b32 v153, v216, v153
	ds_bpermute_b32 v154, v216, v154
	ds_bpermute_b32 v155, v216, v155
	ds_bpermute_b32 v156, v216, v156
	ds_bpermute_b32 v157, v216, v157
	ds_bpermute_b32 v158, v216, v158
	ds_bpermute_b32 v159, v216, v159
	ds_bpermute_b32 v160, v216, v160
	ds_bpermute_b32 v161, v216, v161
	ds_bpermute_b32 v162, v216, v162
	ds_bpermute_b32 v163, v216, v163
	s_waitcnt lgkmcnt(0)
	v_mfma_f32_16x16x32_bf16 v[56:59], v[76:79], v[152:155], v[56:59]
	v_mfma_f32_16x16x32_bf16 v[56:59], v[96:99], v[156:159], v[56:59]
	v_mfma_f32_16x16x32_bf16 v[56:59], v[100:103], v[160:163], v[56:59]
.Lsk1891_b0_mm4:
	s_and_b64 vcc, exec, s[82:83]
	s_cbranch_vccz .Lsk1891_b0_mm5
	ds_bpermute_b32 v164, v216, v164
	ds_bpermute_b32 v165, v216, v165
	ds_bpermute_b32 v166, v216, v166
	ds_bpermute_b32 v167, v216, v167
	ds_bpermute_b32 v168, v216, v168
	ds_bpermute_b32 v169, v216, v169
	ds_bpermute_b32 v170, v216, v170
	ds_bpermute_b32 v171, v216, v171
	ds_bpermute_b32 v172, v216, v172
	ds_bpermute_b32 v173, v216, v173
	ds_bpermute_b32 v174, v216, v174
	ds_bpermute_b32 v175, v216, v175
	s_waitcnt lgkmcnt(0)
	v_mfma_f32_16x16x32_bf16 v[52:55], v[76:79], v[164:167], v[52:55]
	v_mfma_f32_16x16x32_bf16 v[52:55], v[96:99], v[168:171], v[52:55]
	v_mfma_f32_16x16x32_bf16 v[52:55], v[100:103], v[172:175], v[52:55]
.Lsk1891_b0_mm5:
	s_and_b64 vcc, exec, s[84:85]
	s_cbranch_vccz .Lsk1891_b0_mm6
	ds_bpermute_b32 v176, v216, v176
	ds_bpermute_b32 v177, v216, v177
	ds_bpermute_b32 v178, v216, v178
	ds_bpermute_b32 v179, v216, v179
	ds_bpermute_b32 v180, v216, v180
	ds_bpermute_b32 v181, v216, v181
	ds_bpermute_b32 v182, v216, v182
	ds_bpermute_b32 v183, v216, v183
	ds_bpermute_b32 v184, v216, v184
	ds_bpermute_b32 v185, v216, v185
	ds_bpermute_b32 v186, v216, v186
	ds_bpermute_b32 v187, v216, v187
	s_waitcnt lgkmcnt(0)
	v_mfma_f32_16x16x32_bf16 v[48:51], v[76:79], v[176:179], v[48:51]
	v_mfma_f32_16x16x32_bf16 v[48:51], v[96:99], v[180:183], v[48:51]
	v_mfma_f32_16x16x32_bf16 v[48:51], v[100:103], v[184:187], v[48:51]
.Lsk1891_b0_mm6:
	s_and_b64 vcc, exec, s[86:87]
	s_cbranch_vccz .Lsk1891_b0_mm7
	ds_bpermute_b32 v188, v216, v188
	ds_bpermute_b32 v189, v216, v189
	ds_bpermute_b32 v190, v216, v190
	ds_bpermute_b32 v191, v216, v191
	ds_bpermute_b32 v192, v216, v192
	ds_bpermute_b32 v193, v216, v193
	ds_bpermute_b32 v194, v216, v194
	ds_bpermute_b32 v195, v216, v195
	ds_bpermute_b32 v196, v216, v196
	ds_bpermute_b32 v197, v216, v197
	ds_bpermute_b32 v198, v216, v198
	ds_bpermute_b32 v199, v216, v199
	s_waitcnt lgkmcnt(0)
	v_mfma_f32_16x16x32_bf16 v[44:47], v[76:79], v[188:191], v[44:47]
	v_mfma_f32_16x16x32_bf16 v[44:47], v[96:99], v[192:195], v[44:47]
	v_mfma_f32_16x16x32_bf16 v[44:47], v[100:103], v[196:199], v[44:47]

.Lsk1891_b1_ld1:
	v_lshl_add_u64 v[230:231], v[228:229], 0, s[8:9]
	s_and_b64 vcc, exec, s[76:77]
	s_cbranch_vccz .Lsk1891_b1_ld2
	global_load_dwordx4 v[128:131], v[230:231], off
.Lsk1891_b1_ld2:
	v_lshl_add_u64 v[228:229], v[230:231], 0, s[8:9]
	s_and_b64 vcc, exec, s[78:79]
	s_cbranch_vccz .Lsk1891_b1_ld3
	global_load_dwordx4 v[140:143], v[228:229], off
.Lsk1891_b1_ld3:
	v_lshl_add_u64 v[230:231], v[228:229], 0, s[8:9]
	s_and_b64 vcc, exec, s[80:81]
	s_cbranch_vccz .Lsk1891_b1_ld4
	global_load_dwordx4 v[152:155], v[230:231], off
.Lsk1891_b1_ld4:
	v_lshl_add_u64 v[228:229], v[230:231], 0, s[8:9]
	s_and_b64 vcc, exec, s[82:83]
	s_cbranch_vccz .Lsk1891_b1_ld5
	global_load_dwordx4 v[164:167], v[228:229], off
.Lsk1891_b1_ld5:
	v_lshl_add_u64 v[230:231], v[228:229], 0, s[8:9]
	s_and_b64 vcc, exec, s[84:85]
	s_cbranch_vccz .Lsk1891_b1_ld6
	global_load_dwordx4 v[176:179], v[230:231], off
.Lsk1891_b1_ld6:
	v_lshl_add_u64 v[228:229], v[230:231], 0, s[8:9]
	s_and_b64 vcc, exec, s[86:87]
	s_cbranch_vccz .Lsk1891_b1_ld7
	global_load_dwordx4 v[188:191], v[228:229], off

.Lsk1891_b1_mm1:
	s_and_b64 vcc, exec, s[76:77]
	s_cbranch_vccz .Lsk1891_b1_mm2
	ds_bpermute_b32 v128, v216, v128
	ds_bpermute_b32 v129, v216, v129
	ds_bpermute_b32 v130, v216, v130
	ds_bpermute_b32 v131, v216, v131
	s_waitcnt lgkmcnt(0)
	v_mfma_f32_16x16x32_bf16 v[64:67], v[76:79], v[128:131], v[64:67]
.Lsk1891_b1_mm2:
	s_and_b64 vcc, exec, s[78:79]
	s_cbranch_vccz .Lsk1891_b1_mm3
	ds_bpermute_b32 v140, v216, v140
	ds_bpermute_b32 v141, v216, v141
	ds_bpermute_b32 v142, v216, v142
	ds_bpermute_b32 v143, v216, v143
	s_waitcnt lgkmcnt(0)
	v_mfma_f32_16x16x32_bf16 v[60:63], v[76:79], v[140:143], v[60:63]
.Lsk1891_b1_mm3:
	s_and_b64 vcc, exec, s[80:81]
	s_cbranch_vccz .Lsk1891_b1_mm4
	ds_bpermute_b32 v152, v216, v152
	ds_bpermute_b32 v153, v216, v153
	ds_bpermute_b32 v154, v216, v154
	ds_bpermute_b32 v155, v216, v155
	s_waitcnt lgkmcnt(0)
	v_mfma_f32_16x16x32_bf16 v[56:59], v[76:79], v[152:155], v[56:59]
.Lsk1891_b1_mm4:
	s_and_b64 vcc, exec, s[82:83]
	s_cbranch_vccz .Lsk1891_b1_mm5
	ds_bpermute_b32 v164, v216, v164
	ds_bpermute_b32 v165, v216, v165
	ds_bpermute_b32 v166, v216, v166
	ds_bpermute_b32 v167, v216, v167
	s_waitcnt lgkmcnt(0)
	v_mfma_f32_16x16x32_bf16 v[52:55], v[76:79], v[164:167], v[52:55]
.Lsk1891_b1_mm5:
	s_and_b64 vcc, exec, s[84:85]
	s_cbranch_vccz .Lsk1891_b1_mm6
	ds_bpermute_b32 v176, v216, v176
	ds_bpermute_b32 v177, v216, v177
	ds_bpermute_b32 v178, v216, v178
	ds_bpermute_b32 v179, v216, v179
	s_waitcnt lgkmcnt(0)
	v_mfma_f32_16x16x32_bf16 v[48:51], v[76:79], v[176:179], v[48:51]
.Lsk1891_b1_mm6:
	s_and_b64 vcc, exec, s[86:87]
	s_cbranch_vccz .Lsk1891_b1_mm7
	ds_bpermute_b32 v188, v216, v188
	ds_bpermute_b32 v189, v216, v189
	ds_bpermute_b32 v190, v216, v190
	ds_bpermute_b32 v191, v216, v191
	s_waitcnt lgkmcnt(0)
	v_mfma_f32_16x16x32_bf16 v[44:47], v[76:79], v[188:191], v[44:47]

.Lsk2053_b0_ld1:
	v_lshl_add_u64 v[230:231], v[228:229], 0, s[8:9]
	s_and_b64 vcc, exec, s[66:67]
	s_cbranch_vccz .Lsk2053_b0_ld2
	global_load_dwordx4 v[128:131], v[230:231], off
	global_load_dwordx4 v[132:135], v[230:231], off offset:512
	global_load_dwordx4 v[136:139], v[230:231], off offset:1024
.Lsk2053_b0_ld2:
	v_lshl_add_u64 v[228:229], v[230:231], 0, s[8:9]
	s_and_b64 vcc, exec, s[76:77]
	s_cbranch_vccz .Lsk2053_b0_ld3
	global_load_dwordx4 v[140:143], v[228:229], off
	global_load_dwordx4 v[144:147], v[228:229], off offset:512
	global_load_dwordx4 v[148:151], v[228:229], off offset:1024
.Lsk2053_b0_ld3:
	v_lshl_add_u64 v[230:231], v[228:229], 0, s[8:9]
	s_and_b64 vcc, exec, s[78:79]
	s_cbranch_vccz .Lsk2053_b0_ld4
	global_load_dwordx4 v[152:155], v[230:231], off
	global_load_dwordx4 v[156:159], v[230:231], off offset:512
	global_load_dwordx4 v[160:163], v[230:231], off offset:1024
.Lsk2053_b0_ld4:
	v_lshl_add_u64 v[228:229], v[230:231], 0, s[8:9]
	s_and_b64 vcc, exec, s[80:81]
	s_cbranch_vccz .Lsk2053_b0_ld5
	global_load_dwordx4 v[164:167], v[228:229], off
	global_load_dwordx4 v[168:171], v[228:229], off offset:512
	global_load_dwordx4 v[172:175], v[228:229], off offset:1024
.Lsk2053_b0_ld5:
	v_lshl_add_u64 v[230:231], v[228:229], 0, s[8:9]
	s_and_b64 vcc, exec, s[82:83]
	s_cbranch_vccz .Lsk2053_b0_ld6
	global_load_dwordx4 v[176:179], v[230:231], off
	global_load_dwordx4 v[180:183], v[230:231], off offset:512
	global_load_dwordx4 v[184:187], v[230:231], off offset:1024
.Lsk2053_b0_ld6:
	v_lshl_add_u64 v[228:229], v[230:231], 0, s[8:9]
	s_and_b64 vcc, exec, s[84:85]
	s_cbranch_vccz .Lsk2053_b0_ld7
	global_load_dwordx4 v[188:191], v[228:229], off
	global_load_dwordx4 v[192:195], v[228:229], off offset:512
	global_load_dwordx4 v[196:199], v[228:229], off offset:1024

.Lsk2053_b0_mm1:
	s_and_b64 vcc, exec, s[66:67]
	s_cbranch_vccz .Lsk2053_b0_mm2
	ds_bpermute_b32 v128, v216, v128
	ds_bpermute_b32 v129, v216, v129
	ds_bpermute_b32 v130, v216, v130
	ds_bpermute_b32 v131, v216, v131
	ds_bpermute_b32 v132, v216, v132
	ds_bpermute_b32 v133, v216, v133
	ds_bpermute_b32 v134, v216, v134
	ds_bpermute_b32 v135, v216, v135
	ds_bpermute_b32 v136, v216, v136
	ds_bpermute_b32 v137, v216, v137
	ds_bpermute_b32 v138, v216, v138
	ds_bpermute_b32 v139, v216, v139
	s_waitcnt lgkmcnt(0)
	v_mfma_f32_16x16x32_bf16 v[64:67], v[76:79], v[128:131], v[64:67]
	v_mfma_f32_16x16x32_bf16 v[64:67], v[96:99], v[132:135], v[64:67]
	v_mfma_f32_16x16x32_bf16 v[64:67], v[100:103], v[136:139], v[64:67]
.Lsk2053_b0_mm2:
	s_and_b64 vcc, exec, s[76:77]
	s_cbranch_vccz .Lsk2053_b0_mm3
	ds_bpermute_b32 v140, v216, v140
	ds_bpermute_b32 v141, v216, v141
	ds_bpermute_b32 v142, v216, v142
	ds_bpermute_b32 v143, v216, v143
	ds_bpermute_b32 v144, v216, v144
	ds_bpermute_b32 v145, v216, v145
	ds_bpermute_b32 v146, v216, v146
	ds_bpermute_b32 v147, v216, v147
	ds_bpermute_b32 v148, v216, v148
	ds_bpermute_b32 v149, v216, v149
	ds_bpermute_b32 v150, v216, v150
	ds_bpermute_b32 v151, v216, v151
	s_waitcnt lgkmcnt(0)
	v_mfma_f32_16x16x32_bf16 v[60:63], v[76:79], v[140:143], v[60:63]
	v_mfma_f32_16x16x32_bf16 v[60:63], v[96:99], v[144:147], v[60:63]
	v_mfma_f32_16x16x32_bf16 v[60:63], v[100:103], v[148:151], v[60:63]
.Lsk2053_b0_mm3:
	s_and_b64 vcc, exec, s[78:79]
	s_cbranch_vccz .Lsk2053_b0_mm4
	ds_bpermute_b32 v152, v216, v152
	ds_bpermute_b32 v153, v216, v153
	ds_bpermute_b32 v154, v216, v154
	ds_bpermute_b32 v155, v216, v155
	ds_bpermute_b32 v156, v216, v156
	ds_bpermute_b32 v157, v216, v157
	ds_bpermute_b32 v158, v216, v158
	ds_bpermute_b32 v159, v216, v159
	ds_bpermute_b32 v160, v216, v160
	ds_bpermute_b32 v161, v216, v161
	ds_bpermute_b32 v162, v216, v162
	ds_bpermute_b32 v163, v216, v163
	s_waitcnt lgkmcnt(0)
	v_mfma_f32_16x16x32_bf16 v[56:59], v[76:79], v[152:155], v[56:59]
	v_mfma_f32_16x16x32_bf16 v[56:59], v[96:99], v[156:159], v[56:59]
	v_mfma_f32_16x16x32_bf16 v[56:59], v[100:103], v[160:163], v[56:59]
.Lsk2053_b0_mm4:
	s_and_b64 vcc, exec, s[80:81]
	s_cbranch_vccz .Lsk2053_b0_mm5
	ds_bpermute_b32 v164, v216, v164
	ds_bpermute_b32 v165, v216, v165
	ds_bpermute_b32 v166, v216, v166
	ds_bpermute_b32 v167, v216, v167
	ds_bpermute_b32 v168, v216, v168
	ds_bpermute_b32 v169, v216, v169
	ds_bpermute_b32 v170, v216, v170
	ds_bpermute_b32 v171, v216, v171
	ds_bpermute_b32 v172, v216, v172
	ds_bpermute_b32 v173, v216, v173
	ds_bpermute_b32 v174, v216, v174
	ds_bpermute_b32 v175, v216, v175
	s_waitcnt lgkmcnt(0)
	v_mfma_f32_16x16x32_bf16 v[52:55], v[76:79], v[164:167], v[52:55]
	v_mfma_f32_16x16x32_bf16 v[52:55], v[96:99], v[168:171], v[52:55]
	v_mfma_f32_16x16x32_bf16 v[52:55], v[100:103], v[172:175], v[52:55]
.Lsk2053_b0_mm5:
	s_and_b64 vcc, exec, s[82:83]
	s_cbranch_vccz .Lsk2053_b0_mm6
	ds_bpermute_b32 v176, v216, v176
	ds_bpermute_b32 v177, v216, v177
	ds_bpermute_b32 v178, v216, v178
	ds_bpermute_b32 v179, v216, v179
	ds_bpermute_b32 v180, v216, v180
	ds_bpermute_b32 v181, v216, v181
	ds_bpermute_b32 v182, v216, v182
	ds_bpermute_b32 v183, v216, v183
	ds_bpermute_b32 v184, v216, v184
	ds_bpermute_b32 v185, v216, v185
	ds_bpermute_b32 v186, v216, v186
	ds_bpermute_b32 v187, v216, v187
	s_waitcnt lgkmcnt(0)
	v_mfma_f32_16x16x32_bf16 v[48:51], v[76:79], v[176:179], v[48:51]
	v_mfma_f32_16x16x32_bf16 v[48:51], v[96:99], v[180:183], v[48:51]
	v_mfma_f32_16x16x32_bf16 v[48:51], v[100:103], v[184:187], v[48:51]
.Lsk2053_b0_mm6:
	s_and_b64 vcc, exec, s[84:85]
	s_cbranch_vccz .Lsk2053_b0_mm7
	ds_bpermute_b32 v188, v216, v188
	ds_bpermute_b32 v189, v216, v189
	ds_bpermute_b32 v190, v216, v190
	ds_bpermute_b32 v191, v216, v191
	ds_bpermute_b32 v192, v216, v192
	ds_bpermute_b32 v193, v216, v193
	ds_bpermute_b32 v194, v216, v194
	ds_bpermute_b32 v195, v216, v195
	ds_bpermute_b32 v196, v216, v196
	ds_bpermute_b32 v197, v216, v197
	ds_bpermute_b32 v198, v216, v198
	ds_bpermute_b32 v199, v216, v199
	s_waitcnt lgkmcnt(0)
	v_mfma_f32_16x16x32_bf16 v[44:47], v[76:79], v[188:191], v[44:47]
	v_mfma_f32_16x16x32_bf16 v[44:47], v[96:99], v[192:195], v[44:47]
	v_mfma_f32_16x16x32_bf16 v[44:47], v[100:103], v[196:199], v[44:47]

.Lsk2053_b1_ld1:
	v_lshl_add_u64 v[230:231], v[228:229], 0, s[8:9]
	s_and_b64 vcc, exec, s[66:67]
	s_cbranch_vccz .Lsk2053_b1_ld2
	global_load_dwordx4 v[128:131], v[230:231], off
.Lsk2053_b1_ld2:
	v_lshl_add_u64 v[228:229], v[230:231], 0, s[8:9]
	s_and_b64 vcc, exec, s[76:77]
	s_cbranch_vccz .Lsk2053_b1_ld3
	global_load_dwordx4 v[140:143], v[228:229], off
.Lsk2053_b1_ld3:
	v_lshl_add_u64 v[230:231], v[228:229], 0, s[8:9]
	s_and_b64 vcc, exec, s[78:79]
	s_cbranch_vccz .Lsk2053_b1_ld4
	global_load_dwordx4 v[152:155], v[230:231], off
.Lsk2053_b1_ld4:
	v_lshl_add_u64 v[228:229], v[230:231], 0, s[8:9]
	s_and_b64 vcc, exec, s[80:81]
	s_cbranch_vccz .Lsk2053_b1_ld5
	global_load_dwordx4 v[164:167], v[228:229], off
.Lsk2053_b1_ld5:
	v_lshl_add_u64 v[230:231], v[228:229], 0, s[8:9]
	s_and_b64 vcc, exec, s[82:83]
	s_cbranch_vccz .Lsk2053_b1_ld6
	global_load_dwordx4 v[176:179], v[230:231], off
.Lsk2053_b1_ld6:
	v_lshl_add_u64 v[228:229], v[230:231], 0, s[8:9]
	s_and_b64 vcc, exec, s[84:85]
	s_cbranch_vccz .Lsk2053_b1_ld7
	global_load_dwordx4 v[188:191], v[228:229], off

.Lsk2053_b1_mm1:
	s_and_b64 vcc, exec, s[66:67]
	s_cbranch_vccz .Lsk2053_b1_mm2
	ds_bpermute_b32 v128, v216, v128
	ds_bpermute_b32 v129, v216, v129
	ds_bpermute_b32 v130, v216, v130
	ds_bpermute_b32 v131, v216, v131
	s_waitcnt lgkmcnt(0)
	v_mfma_f32_16x16x32_bf16 v[64:67], v[76:79], v[128:131], v[64:67]
.Lsk2053_b1_mm2:
	s_and_b64 vcc, exec, s[76:77]
	s_cbranch_vccz .Lsk2053_b1_mm3
	ds_bpermute_b32 v140, v216, v140
	ds_bpermute_b32 v141, v216, v141
	ds_bpermute_b32 v142, v216, v142
	ds_bpermute_b32 v143, v216, v143
	s_waitcnt lgkmcnt(0)
	v_mfma_f32_16x16x32_bf16 v[60:63], v[76:79], v[140:143], v[60:63]
.Lsk2053_b1_mm3:
	s_and_b64 vcc, exec, s[78:79]
	s_cbranch_vccz .Lsk2053_b1_mm4
	ds_bpermute_b32 v152, v216, v152
	ds_bpermute_b32 v153, v216, v153
	ds_bpermute_b32 v154, v216, v154
	ds_bpermute_b32 v155, v216, v155
	s_waitcnt lgkmcnt(0)
	v_mfma_f32_16x16x32_bf16 v[56:59], v[76:79], v[152:155], v[56:59]
.Lsk2053_b1_mm4:
	s_and_b64 vcc, exec, s[80:81]
	s_cbranch_vccz .Lsk2053_b1_mm5
	ds_bpermute_b32 v164, v216, v164
	ds_bpermute_b32 v165, v216, v165
	ds_bpermute_b32 v166, v216, v166
	ds_bpermute_b32 v167, v216, v167
	s_waitcnt lgkmcnt(0)
	v_mfma_f32_16x16x32_bf16 v[52:55], v[76:79], v[164:167], v[52:55]
.Lsk2053_b1_mm5:
	s_and_b64 vcc, exec, s[82:83]
	s_cbranch_vccz .Lsk2053_b1_mm6
	ds_bpermute_b32 v176, v216, v176
	ds_bpermute_b32 v177, v216, v177
	ds_bpermute_b32 v178, v216, v178
	ds_bpermute_b32 v179, v216, v179
	s_waitcnt lgkmcnt(0)
	v_mfma_f32_16x16x32_bf16 v[48:51], v[76:79], v[176:179], v[48:51]
.Lsk2053_b1_mm6:
	s_and_b64 vcc, exec, s[84:85]
	s_cbranch_vccz .Lsk2053_b1_mm7
	ds_bpermute_b32 v188, v216, v188
	ds_bpermute_b32 v189, v216, v189
	ds_bpermute_b32 v190, v216, v190
	ds_bpermute_b32 v191, v216, v191
	s_waitcnt lgkmcnt(0)
	v_mfma_f32_16x16x32_bf16 v[44:47], v[76:79], v[188:191], v[44:47]

.LBB0_2461:
	v_mbcnt_lo_u32_b32 v212, -1, 0
	v_mbcnt_hi_u32_b32 v212, -1, v212
	v_lshrrev_b32_e32 v214, 2, v212
	v_and_b32_e32 v215, 15, v212
	v_sub_u32_e32 v214, v214, v215
	v_mul_i32_i24_e32 v214, 0x2000, v214
	v_lshlrev_b32_e32 v216, 4, v215
	v_and_b32_e32 v215, 3, v212
	v_lshrrev_b32_e32 v212, 4, v212
	v_sub_u32_e32 v215, v215, v212
	v_lshl_add_u32 v214, v215, 4, v214
	v_lshl_add_u32 v216, v212, 2, v216
	v_ashrrev_i32_e32 v215, 31, v214
	s_lshl_b32 s6, s2, 1
	s_mov_b32 s7, 0
	v_lshl_add_u64 v[218:219], v[82:83], 0, v[214:215]
	v_lshl_add_u64 v[214:215], v[80:81], 0, v[214:215]
	v_lshl_add_u64 v[218:219], v[218:219], 0, s[6:7]
	v_lshl_add_u64 v[214:215], v[214:215], 0, s[6:7]
	s_mov_b64 s[8:9], 0x20000
	global_load_dwordx4 v[76:79], v[218:219], off
	global_load_dwordx4 v[96:99], v[218:219], off offset:512
	global_load_dwordx4 v[100:103], v[218:219], off offset:1024
	s_and_b64 vcc, exec, s[28:29]
	s_cbranch_vccz .Lsk2461_b0_ld0
	global_load_dwordx4 v[104:107], v[214:215], off
	global_load_dwordx4 v[108:111], v[214:215], off offset:512
	global_load_dwordx4 v[112:115], v[214:215], off offset:1024

.Lsk2461_b0_mm8:
	s_mov_b64 s[6:7], 0x600
	v_lshl_add_u64 v[218:219], v[218:219], 0, s[6:7]
	v_lshl_add_u64 v[214:215], v[214:215], 0, s[6:7]
	global_load_dwordx4 v[76:79], v[218:219], off
	global_load_dwordx4 v[96:99], v[218:219], off offset:512
	global_load_dwordx4 v[100:103], v[218:219], off offset:1024
	s_and_b64 vcc, exec, s[28:29]
	s_cbranch_vccz .Lsk2461_b1_ld0
	global_load_dwordx4 v[104:107], v[214:215], off
	global_load_dwordx4 v[108:111], v[214:215], off offset:512
	global_load_dwordx4 v[112:115], v[214:215], off offset:1024

.Lsk2675_b0_ld1:
	v_lshl_add_u64 v[230:231], v[228:229], 0, s[8:9]
	s_and_b64 vcc, exec, s[34:35]
	s_cbranch_vccz .Lsk2675_b0_ld2
	global_load_dwordx4 v[128:131], v[230:231], off
	global_load_dwordx4 v[132:135], v[230:231], off offset:512
	global_load_dwordx4 v[136:139], v[230:231], off offset:1024
.Lsk2675_b0_ld2:
	v_lshl_add_u64 v[228:229], v[230:231], 0, s[8:9]
	s_and_b64 vcc, exec, s[90:91]
	s_cbranch_vccz .Lsk2675_b0_ld3
	global_load_dwordx4 v[140:143], v[228:229], off
	global_load_dwordx4 v[144:147], v[228:229], off offset:512
	global_load_dwordx4 v[148:151], v[228:229], off offset:1024
.Lsk2675_b0_ld3:
	v_lshl_add_u64 v[230:231], v[228:229], 0, s[8:9]
	s_and_b64 vcc, exec, s[92:93]
	s_cbranch_vccz .Lsk2675_b0_ld4
	global_load_dwordx4 v[152:155], v[230:231], off
	global_load_dwordx4 v[156:159], v[230:231], off offset:512
	global_load_dwordx4 v[160:163], v[230:231], off offset:1024
.Lsk2675_b0_ld4:
	v_lshl_add_u64 v[228:229], v[230:231], 0, s[8:9]
	s_and_b64 vcc, exec, s[94:95]
	s_cbranch_vccz .Lsk2675_b0_ld5
	global_load_dwordx4 v[164:167], v[228:229], off
	global_load_dwordx4 v[168:171], v[228:229], off offset:512
	global_load_dwordx4 v[172:175], v[228:229], off offset:1024
.Lsk2675_b0_ld5:
	v_lshl_add_u64 v[230:231], v[228:229], 0, s[8:9]
	s_and_b64 vcc, exec, s[96:97]
	s_cbranch_vccz .Lsk2675_b0_ld6
	global_load_dwordx4 v[176:179], v[230:231], off
	global_load_dwordx4 v[180:183], v[230:231], off offset:512
	global_load_dwordx4 v[184:187], v[230:231], off offset:1024
.Lsk2675_b0_ld6:
	v_lshl_add_u64 v[228:229], v[230:231], 0, s[8:9]
	s_and_b64 vcc, exec, s[70:71]
	s_cbranch_vccz .Lsk2675_b0_ld7
	global_load_dwordx4 v[188:191], v[228:229], off
	global_load_dwordx4 v[192:195], v[228:229], off offset:512
	global_load_dwordx4 v[196:199], v[228:229], off offset:1024
.Lsk2675_b0_ld7:
	v_lshl_add_u64 v[230:231], v[228:229], 0, s[8:9]
	s_and_b64 vcc, exec, s[2:3]
	s_cbranch_vccz .Lsk2675_b0_ld8
	global_load_dwordx4 v[200:203], v[230:231], off
	global_load_dwordx4 v[204:207], v[230:231], off offset:512
	global_load_dwordx4 v[208:211], v[230:231], off offset:1024

.Lsk2675_b0_mm1:
	s_and_b64 vcc, exec, s[34:35]
	s_cbranch_vccz .Lsk2675_b0_mm2
	ds_bpermute_b32 v128, v216, v128
	ds_bpermute_b32 v129, v216, v129
	ds_bpermute_b32 v130, v216, v130
	ds_bpermute_b32 v131, v216, v131
	ds_bpermute_b32 v132, v216, v132
	ds_bpermute_b32 v133, v216, v133
	ds_bpermute_b32 v134, v216, v134
	ds_bpermute_b32 v135, v216, v135
	ds_bpermute_b32 v136, v216, v136
	ds_bpermute_b32 v137, v216, v137
	ds_bpermute_b32 v138, v216, v138
	ds_bpermute_b32 v139, v216, v139
	s_waitcnt lgkmcnt(0)
	v_mfma_f32_16x16x32_bf16 v[64:67], v[76:79], v[128:131], v[64:67]
	v_mfma_f32_16x16x32_bf16 v[64:67], v[96:99], v[132:135], v[64:67]
	v_mfma_f32_16x16x32_bf16 v[64:67], v[100:103], v[136:139], v[64:67]
.Lsk2675_b0_mm2:
	s_and_b64 vcc, exec, s[90:91]
	s_cbranch_vccz .Lsk2675_b0_mm3
	ds_bpermute_b32 v140, v216, v140
	ds_bpermute_b32 v141, v216, v141
	ds_bpermute_b32 v142, v216, v142
	ds_bpermute_b32 v143, v216, v143
	ds_bpermute_b32 v144, v216, v144
	ds_bpermute_b32 v145, v216, v145
	ds_bpermute_b32 v146, v216, v146
	ds_bpermute_b32 v147, v216, v147
	ds_bpermute_b32 v148, v216, v148
	ds_bpermute_b32 v149, v216, v149
	ds_bpermute_b32 v150, v216, v150
	ds_bpermute_b32 v151, v216, v151
	s_waitcnt lgkmcnt(0)
	v_mfma_f32_16x16x32_bf16 v[60:63], v[76:79], v[140:143], v[60:63]
	v_mfma_f32_16x16x32_bf16 v[60:63], v[96:99], v[144:147], v[60:63]
	v_mfma_f32_16x16x32_bf16 v[60:63], v[100:103], v[148:151], v[60:63]
.Lsk2675_b0_mm3:
	s_and_b64 vcc, exec, s[92:93]
	s_cbranch_vccz .Lsk2675_b0_mm4
	ds_bpermute_b32 v152, v216, v152
	ds_bpermute_b32 v153, v216, v153
	ds_bpermute_b32 v154, v216, v154
	ds_bpermute_b32 v155, v216, v155
	ds_bpermute_b32 v156, v216, v156
	ds_bpermute_b32 v157, v216, v157
	ds_bpermute_b32 v158, v216, v158
	ds_bpermute_b32 v159, v216, v159
	ds_bpermute_b32 v160, v216, v160
	ds_bpermute_b32 v161, v216, v161
	ds_bpermute_b32 v162, v216, v162
	ds_bpermute_b32 v163, v216, v163
	s_waitcnt lgkmcnt(0)
	v_mfma_f32_16x16x32_bf16 v[56:59], v[76:79], v[152:155], v[56:59]
	v_mfma_f32_16x16x32_bf16 v[56:59], v[96:99], v[156:159], v[56:59]
	v_mfma_f32_16x16x32_bf16 v[56:59], v[100:103], v[160:163], v[56:59]
.Lsk2675_b0_mm4:
	s_and_b64 vcc, exec, s[94:95]
	s_cbranch_vccz .Lsk2675_b0_mm5
	ds_bpermute_b32 v164, v216, v164
	ds_bpermute_b32 v165, v216, v165
	ds_bpermute_b32 v166, v216, v166
	ds_bpermute_b32 v167, v216, v167
	ds_bpermute_b32 v168, v216, v168
	ds_bpermute_b32 v169, v216, v169
	ds_bpermute_b32 v170, v216, v170
	ds_bpermute_b32 v171, v216, v171
	ds_bpermute_b32 v172, v216, v172
	ds_bpermute_b32 v173, v216, v173
	ds_bpermute_b32 v174, v216, v174
	ds_bpermute_b32 v175, v216, v175
	s_waitcnt lgkmcnt(0)
	v_mfma_f32_16x16x32_bf16 v[52:55], v[76:79], v[164:167], v[52:55]
	v_mfma_f32_16x16x32_bf16 v[52:55], v[96:99], v[168:171], v[52:55]
	v_mfma_f32_16x16x32_bf16 v[52:55], v[100:103], v[172:175], v[52:55]
.Lsk2675_b0_mm5:
	s_and_b64 vcc, exec, s[96:97]
	s_cbranch_vccz .Lsk2675_b0_mm6
	ds_bpermute_b32 v176, v216, v176
	ds_bpermute_b32 v177, v216, v177
	ds_bpermute_b32 v178, v216, v178
	ds_bpermute_b32 v179, v216, v179
	ds_bpermute_b32 v180, v216, v180
	ds_bpermute_b32 v181, v216, v181
	ds_bpermute_b32 v182, v216, v182
	ds_bpermute_b32 v183, v216, v183
	ds_bpermute_b32 v184, v216, v184
	ds_bpermute_b32 v185, v216, v185
	ds_bpermute_b32 v186, v216, v186
	ds_bpermute_b32 v187, v216, v187
	s_waitcnt lgkmcnt(0)
	v_mfma_f32_16x16x32_bf16 v[48:51], v[76:79], v[176:179], v[48:51]
	v_mfma_f32_16x16x32_bf16 v[48:51], v[96:99], v[180:183], v[48:51]
	v_mfma_f32_16x16x32_bf16 v[48:51], v[100:103], v[184:187], v[48:51]
.Lsk2675_b0_mm6:
	s_and_b64 vcc, exec, s[70:71]
	s_cbranch_vccz .Lsk2675_b0_mm7
	ds_bpermute_b32 v188, v216, v188
	ds_bpermute_b32 v189, v216, v189
	ds_bpermute_b32 v190, v216, v190
	ds_bpermute_b32 v191, v216, v191
	ds_bpermute_b32 v192, v216, v192
	ds_bpermute_b32 v193, v216, v193
	ds_bpermute_b32 v194, v216, v194
	ds_bpermute_b32 v195, v216, v195
	ds_bpermute_b32 v196, v216, v196
	ds_bpermute_b32 v197, v216, v197
	ds_bpermute_b32 v198, v216, v198
	ds_bpermute_b32 v199, v216, v199
	s_waitcnt lgkmcnt(0)
	v_mfma_f32_16x16x32_bf16 v[44:47], v[76:79], v[188:191], v[44:47]
	v_mfma_f32_16x16x32_bf16 v[44:47], v[96:99], v[192:195], v[44:47]
	v_mfma_f32_16x16x32_bf16 v[44:47], v[100:103], v[196:199], v[44:47]
.Lsk2675_b0_mm7:
	s_and_b64 vcc, exec, s[2:3]
	s_cbranch_vccz .Lsk2675_b0_mm8
	ds_bpermute_b32 v200, v216, v200
	ds_bpermute_b32 v201, v216, v201
	ds_bpermute_b32 v202, v216, v202
	ds_bpermute_b32 v203, v216, v203
	ds_bpermute_b32 v204, v216, v204
	ds_bpermute_b32 v205, v216, v205
	ds_bpermute_b32 v206, v216, v206
	ds_bpermute_b32 v207, v216, v207
	ds_bpermute_b32 v208, v216, v208
	ds_bpermute_b32 v209, v216, v209
	ds_bpermute_b32 v210, v216, v210
	ds_bpermute_b32 v211, v216, v211
	s_waitcnt lgkmcnt(0)
	v_mfma_f32_16x16x32_bf16 v[40:43], v[76:79], v[200:203], v[40:43]
	v_mfma_f32_16x16x32_bf16 v[40:43], v[96:99], v[204:207], v[40:43]
	v_mfma_f32_16x16x32_bf16 v[40:43], v[100:103], v[208:211], v[40:43]

.Lsk2675_b1_ld1:
	v_lshl_add_u64 v[230:231], v[228:229], 0, s[8:9]
	s_and_b64 vcc, exec, s[34:35]
	s_cbranch_vccz .Lsk2675_b1_ld2
	global_load_dwordx4 v[128:131], v[230:231], off
.Lsk2675_b1_ld2:
	v_lshl_add_u64 v[228:229], v[230:231], 0, s[8:9]
	s_and_b64 vcc, exec, s[90:91]
	s_cbranch_vccz .Lsk2675_b1_ld3
	global_load_dwordx4 v[140:143], v[228:229], off
.Lsk2675_b1_ld3:
	v_lshl_add_u64 v[230:231], v[228:229], 0, s[8:9]
	s_and_b64 vcc, exec, s[92:93]
	s_cbranch_vccz .Lsk2675_b1_ld4
	global_load_dwordx4 v[152:155], v[230:231], off
.Lsk2675_b1_ld4:
	v_lshl_add_u64 v[228:229], v[230:231], 0, s[8:9]
	s_and_b64 vcc, exec, s[94:95]
	s_cbranch_vccz .Lsk2675_b1_ld5
	global_load_dwordx4 v[164:167], v[228:229], off
.Lsk2675_b1_ld5:
	v_lshl_add_u64 v[230:231], v[228:229], 0, s[8:9]
	s_and_b64 vcc, exec, s[96:97]
	s_cbranch_vccz .Lsk2675_b1_ld6
	global_load_dwordx4 v[176:179], v[230:231], off
.Lsk2675_b1_ld6:
	v_lshl_add_u64 v[228:229], v[230:231], 0, s[8:9]
	s_and_b64 vcc, exec, s[70:71]
	s_cbranch_vccz .Lsk2675_b1_ld7
	global_load_dwordx4 v[188:191], v[228:229], off
.Lsk2675_b1_ld7:
	v_lshl_add_u64 v[230:231], v[228:229], 0, s[8:9]
	s_and_b64 vcc, exec, s[2:3]
	s_cbranch_vccz .Lsk2675_b1_ld8
	global_load_dwordx4 v[200:203], v[230:231], off

.Lsk2675_b1_mm1:
	s_and_b64 vcc, exec, s[34:35]
	s_cbranch_vccz .Lsk2675_b1_mm2
	ds_bpermute_b32 v128, v216, v128
	ds_bpermute_b32 v129, v216, v129
	ds_bpermute_b32 v130, v216, v130
	ds_bpermute_b32 v131, v216, v131
	s_waitcnt lgkmcnt(0)
	v_mfma_f32_16x16x32_bf16 v[64:67], v[76:79], v[128:131], v[64:67]
.Lsk2675_b1_mm2:
	s_and_b64 vcc, exec, s[90:91]
	s_cbranch_vccz .Lsk2675_b1_mm3
	ds_bpermute_b32 v140, v216, v140
	ds_bpermute_b32 v141, v216, v141
	ds_bpermute_b32 v142, v216, v142
	ds_bpermute_b32 v143, v216, v143
	s_waitcnt lgkmcnt(0)
	v_mfma_f32_16x16x32_bf16 v[60:63], v[76:79], v[140:143], v[60:63]
.Lsk2675_b1_mm3:
	s_and_b64 vcc, exec, s[92:93]
	s_cbranch_vccz .Lsk2675_b1_mm4
	ds_bpermute_b32 v152, v216, v152
	ds_bpermute_b32 v153, v216, v153
	ds_bpermute_b32 v154, v216, v154
	ds_bpermute_b32 v155, v216, v155
	s_waitcnt lgkmcnt(0)
	v_mfma_f32_16x16x32_bf16 v[56:59], v[76:79], v[152:155], v[56:59]
.Lsk2675_b1_mm4:
	s_and_b64 vcc, exec, s[94:95]
	s_cbranch_vccz .Lsk2675_b1_mm5
	ds_bpermute_b32 v164, v216, v164
	ds_bpermute_b32 v165, v216, v165
	ds_bpermute_b32 v166, v216, v166
	ds_bpermute_b32 v167, v216, v167
	s_waitcnt lgkmcnt(0)
	v_mfma_f32_16x16x32_bf16 v[52:55], v[76:79], v[164:167], v[52:55]
.Lsk2675_b1_mm5:
	s_and_b64 vcc, exec, s[96:97]
	s_cbranch_vccz .Lsk2675_b1_mm6
	ds_bpermute_b32 v176, v216, v176
	ds_bpermute_b32 v177, v216, v177
	ds_bpermute_b32 v178, v216, v178
	ds_bpermute_b32 v179, v216, v179
	s_waitcnt lgkmcnt(0)
	v_mfma_f32_16x16x32_bf16 v[48:51], v[76:79], v[176:179], v[48:51]
.Lsk2675_b1_mm6:
	s_and_b64 vcc, exec, s[70:71]
	s_cbranch_vccz .Lsk2675_b1_mm7
	ds_bpermute_b32 v188, v216, v188
	ds_bpermute_b32 v189, v216, v189
	ds_bpermute_b32 v190, v216, v190
	ds_bpermute_b32 v191, v216, v191
	s_waitcnt lgkmcnt(0)
	v_mfma_f32_16x16x32_bf16 v[44:47], v[76:79], v[188:191], v[44:47]
.Lsk2675_b1_mm7:
	s_and_b64 vcc, exec, s[2:3]
	s_cbranch_vccz .Lsk2675_b1_mm8
	ds_bpermute_b32 v200, v216, v200
	ds_bpermute_b32 v201, v216, v201
	ds_bpermute_b32 v202, v216, v202
	ds_bpermute_b32 v203, v216, v203
	s_waitcnt lgkmcnt(0)
	v_mfma_f32_16x16x32_bf16 v[40:43], v[76:79], v[200:203], v[40:43]
.Lsk2675_b1_mm8:
	s_branch .LBB0_2712
.LBB0_2711:
	v_mov_b32_e32 v74, v75
	v_mov_b32_e32 v73, v75
	v_mov_b32_e32 v72, v75
	v_mov_b32_e32 v71, v75
	v_mov_b32_e32 v70, v75
	v_mov_b32_e32 v69, v75
	v_mov_b32_e32 v68, v75
	v_mov_b32_e32 v67, v75
	v_mov_b32_e32 v66, v75
	v_mov_b32_e32 v65, v75
	v_mov_b32_e32 v64, v75
	v_mov_b32_e32 v63, v75
	v_mov_b32_e32 v62, v75
	v_mov_b32_e32 v61, v75
	v_mov_b32_e32 v60, v75
	v_mov_b32_e32 v59, v75
	v_mov_b32_e32 v58, v75
	v_mov_b32_e32 v57, v75
	v_mov_b32_e32 v56, v75
	v_mov_b32_e32 v55, v75
	v_mov_b32_e32 v54, v75
	v_mov_b32_e32 v53, v75
	v_mov_b32_e32 v52, v75
	v_mov_b32_e32 v51, v75
	v_mov_b32_e32 v50, v75
	v_mov_b32_e32 v49, v75
	v_mov_b32_e32 v48, v75
	v_mov_b32_e32 v47, v75
	v_mov_b32_e32 v46, v75
	v_mov_b32_e32 v45, v75
	v_mov_b32_e32 v44, v75
	v_mov_b32_e32 v43, v75
	v_mov_b32_e32 v42, v75
	v_mov_b32_e32 v41, v75
	v_mov_b32_e32 v40, v75
	s_branch .LBB0_2713
